# attention main loop regenerated: uniform MFMA/softmax/LDS interleave, double-buffered K fragments, last PV group after the barrier
# speedup vs baseline: 1.0051x; 1.0051x over previous
; __device__ __forceinline__ int v_st(int k, int c) { const int kk = (k & ~0xC) | ((k & 4) << 1) | ((k & 8) >> 1); return ((kk >> 3) * 4 + (c >> 5)) * 512 + ((kk & 7) * 32 + (c & 31)) * 2; }
; __device__ __forceinline__ int v_rd_base(int lane) { return ((lane & 3) << 3) | (((lane >> 2) & 3) << 6) | (((lane >> 4) & 1) << 5) | (((lane >> 5) & 1) << 8); }
; #define SWAIT() asm volatile("s_waitcnt vmcnt(0)" ::: "memory")
; __device__ __forceinline__ void partialSM(f32x16& p0, f32x16& p1, float mnC) {
;   constexpr float C = SCALE * 1.4426950408889634f;
; #pragma unroll
;   for (int r = 0; r < 16; ++r) p0[r] = fmaf(p0[r], C, mnC);
; #pragma unroll
;   for (int r = 0; r < 16; ++r) p1[r] = fmaf(p1[r], C, mnC);
; #pragma unroll
;   for (int r = 0; r < 16; ++r) p0[r] = __builtin_amdgcn_exp2f(p0[r]);
; }
; __device__ __forceinline__ void attn_dense_body(const bf16* __restrict__ Qb, const bf16* __restrict__ Kh, const bf16* __restrict__ Vh,
;                                                 bf16* __restrict__ Ob, int seq, char* lds, const int tid, const float mnC) {
;   const int wid = tid >> 6, lane = tid & 63, r32 = lane & 31, hi = lane >> 5;
;   bf16* V_lds = (bf16*)lds; bf16* K_lds = (bf16*)(lds + 2 * SHM_V);
;   float* ws = (float*)(lds + 2 * SHM_V + 2 * SHM_K) + wid * 64; float* li_l = ws;
;   float l_reg = 0; f32x16 o[4] = {}; bf16x8 qr[8];
;   const bf16* Qw = Qb + (long)(wid * QBLK + r32) * LDQ + hi * 8;
; #pragma unroll
;   for (int d0 = 0; d0 < 8; ++d0) qr[d0] = ld8(Qw + d0 * 16);
;   const int sr = tid >> 4, sc = (tid & 15) * 8, vst0 = v_st(sr, sc), vst1 = v_st(32 + sr, sc);
;   const int vb0 = (int)(uintptr_t)V_lds + v_rd_base(lane);
;   bf16x8 s0_vs0, s0_vs1, s0_ks0, s0_ks1;
;     ...
;   f32x16 pA0, pA1, pB0, pB1; bf16x8 pa0, pa1, pa2, pa3; const int NT = seq / KVBLK;
;   SLOAD0(0);
;   bf16x8 t1_vs0 = ld8(&Vh[(long)(KVBLK + sr) * LDK + sc]), t1_vs1 = ld8(&Vh[(long)(KVBLK + 32 + sr) * LDK + sc]);
;   bf16x8 t1_ks0 = ld8(&Kh[(long)(KVBLK + sr) * LDK + sc]), t1_ks1 = ld8(&Kh[(long)(KVBLK + 32 + sr) * LDK + sc]);
;   asm volatile("s_waitcnt vmcnt(4)" ::: "memory"); SWRITE0(0); __syncthreads();
;   qkt(pA0, pA1, K_lds, qr, r32, hi); partialSM(pA0, pA1, mnC);
;   s0_vs0 = t1_vs0; s0_vs1 = t1_vs1; s0_ks0 = t1_ks0; s0_ks1 = t1_ks1;
;   SWAIT(); SWRITE0(1); __syncthreads();
;   if (__builtin_amdgcn_readfirstlane(wid) >= 4) __builtin_amdgcn_s_setprio(1);
.LBB0_1039:
	s_lshr_b32 s12, s8, 2
	v_and_b32_e32 v159, 63, v174
	s_and_b32 s12, s12, 1
	s_and_b32 s13, s4, 3
	v_mov_b32_e32 v153, v152
	s_nop 5
	v_pk_fma_f32 v[168:169], v[0:1], s[26:27], v[156:157] op_sel_hi:[1,0,1]
	s_mul_i32 s12, s12, 0x840000
	s_lshl_b32 s13, s13, 8
	v_lshlrev_b32_e32 v1, 4, v159
	v_pk_fma_f32 v[166:167], v[2:3], s[26:27], v[152:153] op_sel_hi:[1,0,1]
	s_or_b32 s13, s13, s12
	v_lshlrev_b32_e32 v0, 3, v159
	v_and_b32_e32 v1, 0xc0, v1
	v_lshlrev_b32_e32 v2, 1, v159
	v_and_or_b32 v1, v0, 24, v1
	v_and_b32_e32 v2, 32, v2
	v_and_b32_e32 v0, 0x100, v0
	s_cmp_lg_u32 0, -1
	v_or3_b32 v0, v1, v2, v0
	s_cselect_b32 s14, 0, 0
	v_fmamk_f32 v16, v16, 0x3e0293ee, v152
	v_fmamk_f32 v17, v17, 0x3e0293ee, v152
	v_fmamk_f32 v18, v18, 0x3e0293ee, v152
	v_fmamk_f32 v19, v19, 0x3e0293ee, v152
	v_fmamk_f32 v20, v20, 0x3e0293ee, v152
	v_fmamk_f32 v21, v21, 0x3e0293ee, v152
	v_fmamk_f32 v22, v22, 0x3e0293ee, v152
	v_fmamk_f32 v23, v23, 0x3e0293ee, v152
	v_fmamk_f32 v24, v24, 0x3e0293ee, v152
	v_fmamk_f32 v25, v25, 0x3e0293ee, v152
	v_fmamk_f32 v26, v26, 0x3e0293ee, v152
	v_fmamk_f32 v27, v27, 0x3e0293ee, v152
	v_fmamk_f32 v28, v28, 0x3e0293ee, v152
	v_fmamk_f32 v29, v29, 0x3e0293ee, v152
	v_fmamk_f32 v30, v30, 0x3e0293ee, v152
	v_fmamk_f32 v31, v31, 0x3e0293ee, v152
	v_add_u32_e32 v173, s14, v0
	s_addk_i32 s14, 0x4000
	v_pk_fma_f32 v[144:145], v[14:15], s[26:27], v[152:153] op_sel_hi:[1,0,1]
	v_pk_fma_f32 v[146:147], v[12:13], s[26:27], v[152:153] op_sel_hi:[1,0,1]
	v_pk_fma_f32 v[148:149], v[10:11], s[26:27], v[152:153] op_sel_hi:[1,0,1]
	v_pk_fma_f32 v[162:163], v[8:9], s[26:27], v[152:153] op_sel_hi:[1,0,1]
	v_pk_fma_f32 v[150:151], v[6:7], s[26:27], v[152:153] op_sel_hi:[1,0,1]
	v_pk_fma_f32 v[164:165], v[4:5], s[26:27], v[152:153] op_sel_hi:[1,0,1]
	v_exp_f32_e32 v199, v16
	v_exp_f32_e32 v201, v17
	v_exp_f32_e32 v198, v18
	v_exp_f32_e32 v203, v19
	v_exp_f32_e32 v200, v20
	v_exp_f32_e32 v202, v21
	v_exp_f32_e32 v196, v22
	v_exp_f32_e32 v197, v23
	v_exp_f32_e32 v193, v24
	v_exp_f32_e32 v195, v25
	v_exp_f32_e32 v192, v26
	v_exp_f32_e32 v194, v27
	v_exp_f32_e32 v189, v28
	v_exp_f32_e32 v191, v29
	v_exp_f32_e32 v188, v30
	v_exp_f32_e32 v190, v31
	v_add_u32_e32 v153, s14, v0
	v_and_b32_e32 v0, 15, v174
	s_add_u32 s14, s2, s13
	v_lshl_or_b32 v32, v0, 4, v32
	s_addc_u32 s15, s3, 0
	v_lshl_add_u64 v[0:1], s[14:15], 0, v[32:33]
	s_mov_b64 s[14:15], 0xeb38000
	v_mov_b32_e32 v187, 0
	s_mov_b32 s12, -1
	v_lshl_add_u64 v[160:161], v[0:1], 0, s[14:15]
	v_mov_b32_e32 v0, 0
	v_mov_b32_e32 v1, v187
	v_mov_b32_e32 v2, v187
	v_mov_b32_e32 v3, v187
	v_mov_b32_e32 v4, v187
	v_mov_b32_e32 v5, v187
	v_mov_b32_e32 v6, v187
	v_mov_b32_e32 v7, v187
	v_mov_b32_e32 v8, v187
	v_mov_b32_e32 v9, v187
	v_mov_b32_e32 v10, v187
	v_mov_b32_e32 v11, v187
	v_mov_b32_e32 v12, v187
	v_mov_b32_e32 v13, v187
	v_mov_b32_e32 v14, v187
	v_mov_b32_e32 v15, v187
	v_mov_b32_e32 v16, 0
	v_mov_b32_e32 v17, v187
	v_mov_b32_e32 v18, v187
	v_mov_b32_e32 v19, v187
	v_mov_b32_e32 v20, v187
	v_mov_b32_e32 v21, v187
	v_mov_b32_e32 v22, v187
	v_mov_b32_e32 v23, v187
	v_mov_b32_e32 v24, v187
	v_mov_b32_e32 v25, v187
	v_mov_b32_e32 v26, v187
	v_mov_b32_e32 v27, v187
	v_mov_b32_e32 v28, v187
	v_mov_b32_e32 v29, v187
	v_mov_b32_e32 v30, v187
	v_mov_b32_e32 v31, v187
	v_mov_b32_e32 v32, 0
	v_mov_b32_e32 v33, v187
	v_mov_b32_e32 v34, v187
	v_mov_b32_e32 v35, v187
	v_mov_b32_e32 v36, v187
	v_mov_b32_e32 v37, v187
	v_mov_b32_e32 v38, v187
	v_mov_b32_e32 v39, v187
	v_mov_b32_e32 v40, v187
	v_mov_b32_e32 v41, v187
	v_mov_b32_e32 v42, v187
	v_mov_b32_e32 v43, v187
	v_mov_b32_e32 v44, v187
	v_mov_b32_e32 v45, v187
	v_mov_b32_e32 v46, v187
	v_mov_b32_e32 v47, v187
	v_mov_b32_e32 v48, 0
	v_mov_b32_e32 v49, v187
	v_mov_b32_e32 v50, v187
	v_mov_b32_e32 v51, v187
	v_mov_b32_e32 v52, v187
	v_mov_b32_e32 v53, v187
	v_mov_b32_e32 v54, v187
	v_mov_b32_e32 v55, v187
	v_mov_b32_e32 v56, v187
	v_mov_b32_e32 v57, v187
	v_mov_b32_e32 v58, v187
	v_mov_b32_e32 v59, v187
	v_mov_b32_e32 v60, v187
	v_mov_b32_e32 v61, v187
	v_mov_b32_e32 v62, v187
	v_mov_b32_e32 v63, v187
	v_lshrrev_b32_e32 v216, 6, v174
	v_lshrrev_b32_e32 v217, 4, v159
	v_and_b32_e32 v218, 15, v159
	v_readfirstlane_b32 s98, v216
	v_xor_b32_e32 v218, v218, v217
	v_lshlrev_b32_e32 v218, 4, v218
	v_lshl_or_b32 v218, v217, 10, v218
	v_lshl_or_b32 v216, v216, 13, v218
	v_xor_b32_e32 v217, 64, v216
	v_add_u32_e32 v217, 0x1000, v217
	s_and_b32 s99, s98, 1
	s_lshl_b32 s99, s99, 2
	s_lshr_b32 s100, s98, 1
	s_lshl_b32 s100, s100, 4
	s_or_b32 s99, s99, s100
	s_lshl_b32 s99, s99, 10
	v_bfe_u32 v218, v159, 2, 2
	v_bfe_u32 v219, v159, 4, 1
	v_lshl_or_b32 v218, v219, 3, v218
	v_lshlrev_b32_e32 v218, 10, v218
	v_lshrrev_b32_e32 v219, 5, v159
	v_lshl_or_b32 v218, v219, 6, v218
	v_and_b32_e32 v219, 3, v159
	v_lshl_or_b32 v218, v219, 4, v218
	v_add_u32_e32 v218, s99, v218
	v_add_u32_e32 v219, 0x80, v218
	s_lshl_b32 s98, s98, 11
	s_bfe_u32 s100, s8, 0x10002
	s_mul_i32 s100, s100, 0x840000
	s_and_b32 s101, s8, 3
	s_lshl_b32 s101, s101, 8
	s_add_u32 s100, s100, s101
	s_add_u32 s14, s2, s100
	s_addc_u32 s15, s3, 0
	s_add_u32 s16, s14, 0xeb10000
	s_addc_u32 s17, s15, 0
	s_add_u32 s14, s14, 0xda20000
	s_addc_u32 s15, s15, 0
	v_mov_b32_e32 v136, 0
	v_mov_b32_e32 v137, 0
	v_mov_b32_e32 v138, 0
	v_mov_b32_e32 v139, 0
	v_mov_b32_e32 v140, 0
	v_mov_b32_e32 v141, 0
	v_mov_b32_e32 v142, 0
	v_mov_b32_e32 v143, 0
	v_mov_b32_e32 v208, 0
	v_mov_b32_e32 v209, 0
	v_mov_b32_e32 v210, 0
	v_mov_b32_e32 v211, 0
	v_mov_b32_e32 v228, 0
	v_mov_b32_e32 v229, 0
	v_mov_b32_e32 v230, 0
	v_mov_b32_e32 v231, 0
	v_mov_b32_e32 v232, 0
	v_mov_b32_e32 v233, 0
	v_mov_b32_e32 v234, 0
	v_mov_b32_e32 v235, 0
	v_mov_b32_e32 v236, 0
	v_mov_b32_e32 v237, 0
	v_mov_b32_e32 v238, 0
	v_mov_b32_e32 v239, 0
	v_mov_b32_e32 v240, 0
	v_mov_b32_e32 v241, 0
	v_mov_b32_e32 v242, 0
	v_mov_b32_e32 v243, 0
	v_mov_b32_e32 v204, 0
	v_mov_b32_e32 v205, 0
	v_mov_b32_e32 v206, 0
	v_mov_b32_e32 v207, 0
; __device__ __forceinline__ void finishSM(f32x16& p0, f32x16& p1, float& l_reg, bf16x8& pa0, bf16x8& pa1, bf16x8& pa2, bf16x8& pa3) {
; #pragma unroll
;   for (int r = 0; r < 16; ++r) p1[r] = __builtin_amdgcn_exp2f(p1[r]);
;   float ps = 0;
; #pragma unroll
;   for (int r = 0; r < 16; ++r) ps += p0[r];
; #pragma unroll
;   for (int r = 0; r < 16; ++r) ps += p1[r];
;   l_reg += ps;
;     ...
;   PK4(p0, 0, pa0); PK4(p0, 8, pa1); PK4(p1, 0, pa2); PK4(p1, 8, pa3);
;     ...
; }
; __device__ __forceinline__ void qkt(f32x16& p0, f32x16& p1, const bf16* Ks, const bf16x8* qr, int r32, int hi) {
;   p0 = f32x16{}; p1 = f32x16{};
; #pragma unroll
;   for (int d0 = 0; d0 < 8; ++d0) { int cb = (d0 * 16 + hi * 8) * 2;
;     bf16x8 b0 = *reinterpret_cast<const bf16x8*>((const char*)Ks + KSWZ(r32, cb));
;     bf16x8 b1 = *reinterpret_cast<const bf16x8*>((const char*)Ks + KSWZ(32 + r32, cb));
;     p0 = __builtin_amdgcn_mfma_f32_32x32x16_bf16(b0, qr[d0], p0, 0, 0, 0);
;     p1 = __builtin_amdgcn_mfma_f32_32x32x16_bf16(b1, qr[d0], p1, 0, 0, 0); }
; }
.LBB0_1040:
	ds_read_b128 v[128:131], v179 offset:49152
	ds_read_b128 v[132:135], v179 offset:57344
	ds_read_b128 v[220:223], v182 offset:49152
	ds_read_b128 v[224:227], v182 offset:57344
	v_mfma_f32_32x32x16_bf16 v[48:63], v[136:139], v[232:235], v[48:63]
	s_add_i32 m0, s98, 0x8000
	s_nop 0
	global_load_lds_dwordx4 v216, s[14:15]
	v_mfma_f32_32x32x16_bf16 v[48:63], v[140:143], v[236:239], v[48:63]
	s_add_i32 m0, s98, 0x8400
	s_nop 0
	global_load_lds_dwordx4 v217, s[14:15]
	v_mfma_f32_32x32x16_bf16 v[48:63], v[208:211], v[240:243], v[48:63]
	s_add_i32 m0, s98, 0x4000
	s_nop 0
	global_load_lds_dwordx4 v218, s[16:17]
	v_mfma_f32_32x32x16_bf16 v[48:63], v[228:231], v[204:207], v[48:63]
	s_add_i32 m0, s98, 0x4400
	s_nop 0
	global_load_lds_dwordx4 v219, s[16:17]
	s_add_u32 s14, s14, 0x10000
	s_addc_u32 s15, s15, 0
	s_add_u32 s16, s16, 0x10000
	s_addc_u32 s17, s17, 0
	s_waitcnt lgkmcnt(3)
	v_mfma_f32_32x32x16_bf16 v[80:95], v[128:131], v[124:127], 0
	v_exp_f32_e32 v168, v168
	v_add_f32_e32 v244, v199, v201
	v_cvt_pk_bf16_f32 v136, v199, v201
	v_exp_f32_e32 v169, v169
	v_add_f32_e32 v244, v198, v244
	s_waitcnt lgkmcnt(2)
	v_mfma_f32_32x32x16_bf16 v[64:79], v[132:135], v[124:127], 0
	ds_read_b128 v[128:131], v183 offset:49152
	ds_read_b128 v[132:135], v183 offset:57344
	v_exp_f32_e32 v166, v166
	v_add_f32_e32 v244, v203, v244
	v_cvt_pk_bf16_f32 v137, v198, v203
	v_exp_f32_e32 v167, v167
	v_add_f32_e32 v244, v200, v244
	s_waitcnt lgkmcnt(3)
	v_mfma_f32_32x32x16_bf16 v[80:95], v[220:223], v[120:123], v[80:95]
	v_exp_f32_e32 v164, v164
	v_add_f32_e32 v244, v202, v244
	v_cvt_pk_bf16_f32 v138, v200, v202
	v_exp_f32_e32 v165, v165
	v_add_f32_e32 v244, v196, v244
	s_waitcnt lgkmcnt(2)
	v_mfma_f32_32x32x16_bf16 v[64:79], v[224:227], v[120:123], v[64:79]
	ds_read_b128 v[220:223], v184 offset:49152
	ds_read_b128 v[224:227], v184 offset:57344
	v_exp_f32_e32 v150, v150
	v_add_f32_e32 v244, v197, v244
	v_cvt_pk_bf16_f32 v139, v196, v197
	v_exp_f32_e32 v151, v151
	v_add_f32_e32 v244, v193, v244
	s_waitcnt lgkmcnt(3)
	v_mfma_f32_32x32x16_bf16 v[80:95], v[128:131], v[116:119], v[80:95]
	v_exp_f32_e32 v162, v162
	v_add_f32_e32 v244, v195, v244
	v_cvt_pk_bf16_f32 v140, v193, v195
	v_exp_f32_e32 v163, v163
	v_add_f32_e32 v244, v192, v244
	s_waitcnt lgkmcnt(2)
	v_mfma_f32_32x32x16_bf16 v[64:79], v[132:135], v[116:119], v[64:79]
	ds_read_b128 v[128:131], v185 offset:49152
	ds_read_b128 v[132:135], v185 offset:57344
	v_exp_f32_e32 v148, v148
	v_add_f32_e32 v244, v194, v244
	v_cvt_pk_bf16_f32 v141, v192, v194
	v_exp_f32_e32 v149, v149
	v_add_f32_e32 v244, v189, v244
	s_waitcnt lgkmcnt(3)
	v_mfma_f32_32x32x16_bf16 v[80:95], v[220:223], v[112:115], v[80:95]
	v_exp_f32_e32 v146, v146
	v_add_f32_e32 v244, v191, v244
	v_cvt_pk_bf16_f32 v142, v189, v191
	v_exp_f32_e32 v147, v147
	v_add_f32_e32 v244, v188, v244
	s_waitcnt lgkmcnt(2)
	v_mfma_f32_32x32x16_bf16 v[64:79], v[224:227], v[112:115], v[64:79]
	ds_read_b128 v[220:223], v186 offset:49152
	ds_read_b128 v[224:227], v186 offset:57344
	v_exp_f32_e32 v144, v144
	v_add_f32_e32 v244, v190, v244
	v_cvt_pk_bf16_f32 v143, v188, v190
	v_exp_f32_e32 v145, v145
	v_add_f32_e32 v244, v168, v244
	s_waitcnt lgkmcnt(3)
	v_mfma_f32_32x32x16_bf16 v[80:95], v[128:131], v[108:111], v[80:95]
	v_cvt_pk_bf16_f32 v208, v168, v169
	v_add_f32_e32 v244, v169, v244
	v_permlane32_swap_b32_e32 v136, v138
	v_cvt_pk_bf16_f32 v209, v166, v167
	v_add_f32_e32 v244, v166, v244
	s_waitcnt lgkmcnt(2)
	v_mfma_f32_32x32x16_bf16 v[64:79], v[132:135], v[108:111], v[64:79]
	ds_read_b128 v[128:131], v180 offset:49152
	ds_read_b128 v[132:135], v180 offset:57344
	v_cvt_pk_bf16_f32 v210, v164, v165
	v_add_f32_e32 v244, v167, v244
	v_permlane32_swap_b32_e32 v137, v139
	v_cvt_pk_bf16_f32 v211, v150, v151
	v_add_f32_e32 v244, v164, v244
	s_waitcnt lgkmcnt(3)
	v_mfma_f32_32x32x16_bf16 v[80:95], v[220:223], v[104:107], v[80:95]
	v_cvt_pk_bf16_f32 v228, v162, v163
	v_add_f32_e32 v244, v165, v244
	v_permlane32_swap_b32_e32 v140, v142
	v_cvt_pk_bf16_f32 v229, v148, v149
	v_add_f32_e32 v244, v150, v244
	s_waitcnt lgkmcnt(2)
	v_mfma_f32_32x32x16_bf16 v[64:79], v[224:227], v[104:107], v[64:79]
	ds_read_b128 v[220:223], v181 offset:49152
	ds_read_b128 v[224:227], v181 offset:57344
	v_cvt_pk_bf16_f32 v230, v146, v147
	v_add_f32_e32 v244, v151, v244
	v_permlane32_swap_b32_e32 v141, v143
	v_cvt_pk_bf16_f32 v231, v144, v145
	v_add_f32_e32 v244, v162, v244
	s_waitcnt lgkmcnt(3)
	v_mfma_f32_32x32x16_bf16 v[80:95], v[128:131], v[100:103], v[80:95]
	v_add_f32_e32 v244, v163, v244
	v_permlane32_swap_b32_e32 v208, v210
	v_add_f32_e32 v244, v148, v244
	ds_read_b64_tr_b16 v[232:233], v173 offset:0
	ds_read_b64_tr_b16 v[234:235], v173 offset:2048
	s_waitcnt lgkmcnt(4)
	v_mfma_f32_32x32x16_bf16 v[64:79], v[132:135], v[100:103], v[64:79]
	v_add_f32_e32 v244, v149, v244
	v_permlane32_swap_b32_e32 v209, v211
	v_add_f32_e32 v244, v146, v244
	ds_read_b64_tr_b16 v[236:237], v173 offset:4096
	ds_read_b64_tr_b16 v[238:239], v173 offset:6144
	s_waitcnt lgkmcnt(5)
	v_mfma_f32_32x32x16_bf16 v[80:95], v[220:223], v[96:99], v[80:95]
	v_add_f32_e32 v244, v147, v244
	v_permlane32_swap_b32_e32 v228, v230
	v_add_f32_e32 v244, v144, v244
	ds_read_b64_tr_b16 v[240:241], v173 offset:8192
	ds_read_b64_tr_b16 v[242:243], v173 offset:10240
	s_waitcnt lgkmcnt(6)
	v_mfma_f32_32x32x16_bf16 v[64:79], v[224:227], v[96:99], v[64:79]
	v_add_f32_e32 v244, v145, v244
	v_permlane32_swap_b32_e32 v229, v231
	v_add_f32_e32 v187, v187, v244
	ds_read_b64_tr_b16 v[204:205], v173 offset:12288
	ds_read_b64_tr_b16 v[206:207], v173 offset:14336
	s_waitcnt lgkmcnt(6)
; #define SBAR() __builtin_amdgcn_sched_barrier(0)
; __device__ __forceinline__ void partialSM(f32x16& p0, f32x16& p1, float mnC) {
;   constexpr float C = SCALE * 1.4426950408889634f;
; #pragma unroll
;   for (int r = 0; r < 16; ++r) p0[r] = fmaf(p0[r], C, mnC);
; #pragma unroll
;   for (int r = 0; r < 16; ++r) p1[r] = fmaf(p1[r], C, mnC);
; #pragma unroll
;   for (int r = 0; r < 16; ++r) p0[r] = __builtin_amdgcn_exp2f(p0[r]);
; }
; template <int D0> __device__ __forceinline__ void pv_one(f32x16& od, int vb, bf16x8 pa0, bf16x8 pa1, bf16x8 pa2, bf16x8 pa3) {
;   const s16x4 l0 = tr_read<v_rd_off(D0, 0, 0)>(vb), h0 = tr_read<v_rd_off(D0, 0, 1)>(vb), l1 = tr_read<v_rd_off(D0, 1, 0)>(vb), h1 = tr_read<v_rd_off(D0, 1, 1)>(vb);
;   const s16x4 l2 = tr_read<v_rd_off(D0, 2, 0)>(vb), h2 = tr_read<v_rd_off(D0, 2, 1)>(vb), l3 = tr_read<v_rd_off(D0, 3, 0)>(vb), h3 = tr_read<v_rd_off(D0, 3, 1)>(vb);
;   asm volatile("s_waitcnt lgkmcnt(0)" ::: "memory"); SBAR();
;     ...
;   od = __builtin_amdgcn_mfma_f32_32x32x16_bf16(pa0, PK(l0, h0), od, 0, 0, 0);
;   od = __builtin_amdgcn_mfma_f32_32x32x16_bf16(pa1, PK(l1, h1), od, 0, 0, 0);
;   od = __builtin_amdgcn_mfma_f32_32x32x16_bf16(pa2, PK(l2, h2), od, 0, 0, 0);
;   od = __builtin_amdgcn_mfma_f32_32x32x16_bf16(pa3, PK(l3, h3), od, 0, 0, 0);
;     ...
; }
; __device__ __forceinline__ void pv_d0(f32x16* o, int vb, bf16x8 pa0, bf16x8 pa1, bf16x8 pa2, bf16x8 pa3) {
;   pv_one<0>(o[0], vb, pa0, pa1, pa2, pa3); pv_one<1>(o[1], vb, pa0, pa1, pa2, pa3); pv_one<2>(o[2], vb, pa0, pa1, pa2, pa3); pv_one<3>(o[3], vb, pa0, pa1, pa2, pa3);
; }
	v_mfma_f32_32x32x16_bf16 v[0:15], v[136:139], v[232:235], v[0:15]
	ds_read_b64_tr_b16 v[232:233], v173 offset:512
	ds_read_b64_tr_b16 v[234:235], v173 offset:2560
	v_fmamk_f32 v80, v80, 0x3e0293ee, v152
	v_fmamk_f32 v81, v81, 0x3e0293ee, v152
	v_fmamk_f32 v82, v82, 0x3e0293ee, v152
	v_fmamk_f32 v83, v83, 0x3e0293ee, v152
	s_waitcnt lgkmcnt(6)
	v_mfma_f32_32x32x16_bf16 v[0:15], v[140:143], v[236:239], v[0:15]
	ds_read_b64_tr_b16 v[236:237], v173 offset:4608
	ds_read_b64_tr_b16 v[238:239], v173 offset:6656
	v_fmamk_f32 v84, v84, 0x3e0293ee, v152
	v_fmamk_f32 v85, v85, 0x3e0293ee, v152
	v_fmamk_f32 v86, v86, 0x3e0293ee, v152
	v_fmamk_f32 v87, v87, 0x3e0293ee, v152
	s_waitcnt lgkmcnt(6)
	v_mfma_f32_32x32x16_bf16 v[0:15], v[208:211], v[240:243], v[0:15]
	ds_read_b64_tr_b16 v[240:241], v173 offset:8704
	ds_read_b64_tr_b16 v[242:243], v173 offset:10752
	v_fmamk_f32 v88, v88, 0x3e0293ee, v152
	v_fmamk_f32 v89, v89, 0x3e0293ee, v152
	v_fmamk_f32 v90, v90, 0x3e0293ee, v152
	v_fmamk_f32 v91, v91, 0x3e0293ee, v152
	s_waitcnt lgkmcnt(6)
	v_mfma_f32_32x32x16_bf16 v[0:15], v[228:231], v[204:207], v[0:15]
	ds_read_b64_tr_b16 v[204:205], v173 offset:12800
	ds_read_b64_tr_b16 v[206:207], v173 offset:14848
	v_fmamk_f32 v92, v92, 0x3e0293ee, v152
	v_fmamk_f32 v93, v93, 0x3e0293ee, v152
	v_fmamk_f32 v94, v94, 0x3e0293ee, v152
	v_fmamk_f32 v95, v95, 0x3e0293ee, v152
	s_waitcnt lgkmcnt(6)
	v_mfma_f32_32x32x16_bf16 v[16:31], v[136:139], v[232:235], v[16:31]
	ds_read_b64_tr_b16 v[232:233], v173 offset:1024
	ds_read_b64_tr_b16 v[234:235], v173 offset:3072
	v_exp_f32_e32 v199, v80
	v_fmamk_f32 v168, v64, 0x3e0293ee, v152
	v_exp_f32_e32 v201, v81
	v_fmamk_f32 v169, v65, 0x3e0293ee, v152
	s_waitcnt lgkmcnt(6)
	v_mfma_f32_32x32x16_bf16 v[16:31], v[140:143], v[236:239], v[16:31]
	ds_read_b64_tr_b16 v[236:237], v173 offset:5120
	ds_read_b64_tr_b16 v[238:239], v173 offset:7168
	v_exp_f32_e32 v198, v82
	v_fmamk_f32 v166, v66, 0x3e0293ee, v152
	v_exp_f32_e32 v203, v83
	v_fmamk_f32 v167, v67, 0x3e0293ee, v152
	s_waitcnt lgkmcnt(6)
	v_mfma_f32_32x32x16_bf16 v[16:31], v[208:211], v[240:243], v[16:31]
	ds_read_b64_tr_b16 v[240:241], v173 offset:9216
	ds_read_b64_tr_b16 v[242:243], v173 offset:11264
	v_exp_f32_e32 v200, v84
	v_fmamk_f32 v164, v68, 0x3e0293ee, v152
	v_exp_f32_e32 v202, v85
	v_fmamk_f32 v165, v69, 0x3e0293ee, v152
	s_waitcnt lgkmcnt(6)
	v_mfma_f32_32x32x16_bf16 v[16:31], v[228:231], v[204:207], v[16:31]
	ds_read_b64_tr_b16 v[204:205], v173 offset:13312
	ds_read_b64_tr_b16 v[206:207], v173 offset:15360
	v_exp_f32_e32 v196, v86
	v_fmamk_f32 v150, v70, 0x3e0293ee, v152
	v_exp_f32_e32 v197, v87
	v_fmamk_f32 v151, v71, 0x3e0293ee, v152
	s_waitcnt lgkmcnt(6)
	v_mfma_f32_32x32x16_bf16 v[32:47], v[136:139], v[232:235], v[32:47]
	ds_read_b64_tr_b16 v[232:233], v173 offset:1536
	ds_read_b64_tr_b16 v[234:235], v173 offset:3584
	v_exp_f32_e32 v193, v88
	v_fmamk_f32 v162, v72, 0x3e0293ee, v152
	v_exp_f32_e32 v195, v89
	v_fmamk_f32 v163, v73, 0x3e0293ee, v152
	s_waitcnt lgkmcnt(6)
	v_mfma_f32_32x32x16_bf16 v[32:47], v[140:143], v[236:239], v[32:47]
	ds_read_b64_tr_b16 v[236:237], v173 offset:5632
	ds_read_b64_tr_b16 v[238:239], v173 offset:7680
	v_exp_f32_e32 v192, v90
	v_fmamk_f32 v148, v74, 0x3e0293ee, v152
	v_exp_f32_e32 v194, v91
	v_fmamk_f32 v149, v75, 0x3e0293ee, v152
	s_waitcnt lgkmcnt(6)
	v_mfma_f32_32x32x16_bf16 v[32:47], v[208:211], v[240:243], v[32:47]
	ds_read_b64_tr_b16 v[240:241], v173 offset:9728
	ds_read_b64_tr_b16 v[242:243], v173 offset:11776
	v_exp_f32_e32 v189, v92
	v_fmamk_f32 v146, v76, 0x3e0293ee, v152
	v_exp_f32_e32 v191, v93
	v_fmamk_f32 v147, v77, 0x3e0293ee, v152
	s_waitcnt lgkmcnt(6)
	v_mfma_f32_32x32x16_bf16 v[32:47], v[228:231], v[204:207], v[32:47]
	ds_read_b64_tr_b16 v[204:205], v173 offset:13824
	ds_read_b64_tr_b16 v[206:207], v173 offset:15872
	v_exp_f32_e32 v188, v94
	v_fmamk_f32 v144, v78, 0x3e0293ee, v152
	v_exp_f32_e32 v190, v95
	v_fmamk_f32 v145, v79, 0x3e0293ee, v152
	s_waitcnt vmcnt(0) lgkmcnt(0)
	s_barrier
	ds_read_b128 v[128:131], v179 offset:32768
	ds_read_b128 v[132:135], v179 offset:40960
	ds_read_b128 v[220:223], v182 offset:32768
	ds_read_b128 v[224:227], v182 offset:40960
	v_mfma_f32_32x32x16_bf16 v[48:63], v[136:139], v[232:235], v[48:63]
	s_add_i32 m0, s98, 0xc000
	s_nop 0
	global_load_lds_dwordx4 v216, s[14:15]
	v_mfma_f32_32x32x16_bf16 v[48:63], v[140:143], v[236:239], v[48:63]
	s_add_i32 m0, s98, 0xc400
	s_nop 0
	global_load_lds_dwordx4 v217, s[14:15]
	v_mfma_f32_32x32x16_bf16 v[48:63], v[208:211], v[240:243], v[48:63]
	s_add_i32 m0, s98, 0x0
	s_nop 0
	global_load_lds_dwordx4 v218, s[16:17]
	v_mfma_f32_32x32x16_bf16 v[48:63], v[228:231], v[204:207], v[48:63]
	s_add_i32 m0, s98, 0x400
	s_nop 0
	global_load_lds_dwordx4 v219, s[16:17]
	s_add_u32 s14, s14, 0x10000
	s_addc_u32 s15, s15, 0
	s_add_u32 s16, s16, 0x10000
	s_addc_u32 s17, s17, 0
	s_waitcnt lgkmcnt(3)
	v_mfma_f32_32x32x16_bf16 v[80:95], v[128:131], v[124:127], 0
	v_exp_f32_e32 v168, v168
	v_add_f32_e32 v244, v199, v201
	v_cvt_pk_bf16_f32 v136, v199, v201
	v_exp_f32_e32 v169, v169
	v_add_f32_e32 v244, v198, v244
	s_waitcnt lgkmcnt(2)
	v_mfma_f32_32x32x16_bf16 v[64:79], v[132:135], v[124:127], 0
	ds_read_b128 v[128:131], v183 offset:32768
	ds_read_b128 v[132:135], v183 offset:40960
	v_exp_f32_e32 v166, v166
	v_add_f32_e32 v244, v203, v244
	v_cvt_pk_bf16_f32 v137, v198, v203
	v_exp_f32_e32 v167, v167
	v_add_f32_e32 v244, v200, v244
	s_waitcnt lgkmcnt(3)
	v_mfma_f32_32x32x16_bf16 v[80:95], v[220:223], v[120:123], v[80:95]
	v_exp_f32_e32 v164, v164
	v_add_f32_e32 v244, v202, v244
	v_cvt_pk_bf16_f32 v138, v200, v202
	v_exp_f32_e32 v165, v165
	v_add_f32_e32 v244, v196, v244
	s_waitcnt lgkmcnt(2)
; __device__ __forceinline__ void finishSM(f32x16& p0, f32x16& p1, float& l_reg, bf16x8& pa0, bf16x8& pa1, bf16x8& pa2, bf16x8& pa3) {
; #pragma unroll
;   for (int r = 0; r < 16; ++r) p1[r] = __builtin_amdgcn_exp2f(p1[r]);
;   float ps = 0;
; #pragma unroll
;   for (int r = 0; r < 16; ++r) ps += p0[r];
; #pragma unroll
;   for (int r = 0; r < 16; ++r) ps += p1[r];
;   l_reg += ps;
;     ...
;   PK4(p0, 0, pa0); PK4(p0, 8, pa1); PK4(p1, 0, pa2); PK4(p1, 8, pa3);
;     ...
; }
; __device__ __forceinline__ void qkt(f32x16& p0, f32x16& p1, const bf16* Ks, const bf16x8* qr, int r32, int hi) {
;   p0 = f32x16{}; p1 = f32x16{};
; #pragma unroll
;   for (int d0 = 0; d0 < 8; ++d0) { int cb = (d0 * 16 + hi * 8) * 2;
;     bf16x8 b0 = *reinterpret_cast<const bf16x8*>((const char*)Ks + KSWZ(r32, cb));
;     bf16x8 b1 = *reinterpret_cast<const bf16x8*>((const char*)Ks + KSWZ(32 + r32, cb));
;     p0 = __builtin_amdgcn_mfma_f32_32x32x16_bf16(b0, qr[d0], p0, 0, 0, 0);
;     p1 = __builtin_amdgcn_mfma_f32_32x32x16_bf16(b1, qr[d0], p1, 0, 0, 0); }
; }
	v_mfma_f32_32x32x16_bf16 v[64:79], v[224:227], v[120:123], v[64:79]
	ds_read_b128 v[220:223], v184 offset:32768
	ds_read_b128 v[224:227], v184 offset:40960
	v_exp_f32_e32 v150, v150
	v_add_f32_e32 v244, v197, v244
	v_cvt_pk_bf16_f32 v139, v196, v197
	v_exp_f32_e32 v151, v151
	v_add_f32_e32 v244, v193, v244
	s_waitcnt lgkmcnt(3)
	v_mfma_f32_32x32x16_bf16 v[80:95], v[128:131], v[116:119], v[80:95]
	v_exp_f32_e32 v162, v162
	v_add_f32_e32 v244, v195, v244
	v_cvt_pk_bf16_f32 v140, v193, v195
	v_exp_f32_e32 v163, v163
	v_add_f32_e32 v244, v192, v244
	s_waitcnt lgkmcnt(2)
	v_mfma_f32_32x32x16_bf16 v[64:79], v[132:135], v[116:119], v[64:79]
	ds_read_b128 v[128:131], v185 offset:32768
	ds_read_b128 v[132:135], v185 offset:40960
	v_exp_f32_e32 v148, v148
	v_add_f32_e32 v244, v194, v244
	v_cvt_pk_bf16_f32 v141, v192, v194
	v_exp_f32_e32 v149, v149
	v_add_f32_e32 v244, v189, v244
	s_waitcnt lgkmcnt(3)
	v_mfma_f32_32x32x16_bf16 v[80:95], v[220:223], v[112:115], v[80:95]
	v_exp_f32_e32 v146, v146
	v_add_f32_e32 v244, v191, v244
	v_cvt_pk_bf16_f32 v142, v189, v191
	v_exp_f32_e32 v147, v147
	v_add_f32_e32 v244, v188, v244
	s_waitcnt lgkmcnt(2)
	v_mfma_f32_32x32x16_bf16 v[64:79], v[224:227], v[112:115], v[64:79]
	ds_read_b128 v[220:223], v186 offset:32768
	ds_read_b128 v[224:227], v186 offset:40960
	v_exp_f32_e32 v144, v144
	v_add_f32_e32 v244, v190, v244
	v_cvt_pk_bf16_f32 v143, v188, v190
	v_exp_f32_e32 v145, v145
	v_add_f32_e32 v244, v168, v244
	s_waitcnt lgkmcnt(3)
	v_mfma_f32_32x32x16_bf16 v[80:95], v[128:131], v[108:111], v[80:95]
	v_cvt_pk_bf16_f32 v208, v168, v169
	v_add_f32_e32 v244, v169, v244
	v_permlane32_swap_b32_e32 v136, v138
	v_cvt_pk_bf16_f32 v209, v166, v167
	v_add_f32_e32 v244, v166, v244
	s_waitcnt lgkmcnt(2)
	v_mfma_f32_32x32x16_bf16 v[64:79], v[132:135], v[108:111], v[64:79]
	ds_read_b128 v[128:131], v180 offset:32768
	ds_read_b128 v[132:135], v180 offset:40960
	v_cvt_pk_bf16_f32 v210, v164, v165
	v_add_f32_e32 v244, v167, v244
	v_permlane32_swap_b32_e32 v137, v139
	v_cvt_pk_bf16_f32 v211, v150, v151
	v_add_f32_e32 v244, v164, v244
	s_waitcnt lgkmcnt(3)
	v_mfma_f32_32x32x16_bf16 v[80:95], v[220:223], v[104:107], v[80:95]
	v_cvt_pk_bf16_f32 v228, v162, v163
	v_add_f32_e32 v244, v165, v244
	v_permlane32_swap_b32_e32 v140, v142
	v_cvt_pk_bf16_f32 v229, v148, v149
	v_add_f32_e32 v244, v150, v244
	s_waitcnt lgkmcnt(2)
	v_mfma_f32_32x32x16_bf16 v[64:79], v[224:227], v[104:107], v[64:79]
	ds_read_b128 v[220:223], v181 offset:32768
	ds_read_b128 v[224:227], v181 offset:40960
	v_cvt_pk_bf16_f32 v230, v146, v147
	v_add_f32_e32 v244, v151, v244
	v_permlane32_swap_b32_e32 v141, v143
	v_cvt_pk_bf16_f32 v231, v144, v145
	v_add_f32_e32 v244, v162, v244
	s_waitcnt lgkmcnt(3)
	v_mfma_f32_32x32x16_bf16 v[80:95], v[128:131], v[100:103], v[80:95]
	v_add_f32_e32 v244, v163, v244
	v_permlane32_swap_b32_e32 v208, v210
	v_add_f32_e32 v244, v148, v244
	ds_read_b64_tr_b16 v[232:233], v153 offset:0
	ds_read_b64_tr_b16 v[234:235], v153 offset:2048
	s_waitcnt lgkmcnt(4)
	v_mfma_f32_32x32x16_bf16 v[64:79], v[132:135], v[100:103], v[64:79]
	v_add_f32_e32 v244, v149, v244
	v_permlane32_swap_b32_e32 v209, v211
	v_add_f32_e32 v244, v146, v244
	ds_read_b64_tr_b16 v[236:237], v153 offset:4096
	ds_read_b64_tr_b16 v[238:239], v153 offset:6144
	s_waitcnt lgkmcnt(5)
	v_mfma_f32_32x32x16_bf16 v[80:95], v[220:223], v[96:99], v[80:95]
	v_add_f32_e32 v244, v147, v244
	v_permlane32_swap_b32_e32 v228, v230
	v_add_f32_e32 v244, v144, v244
	ds_read_b64_tr_b16 v[240:241], v153 offset:8192
	ds_read_b64_tr_b16 v[242:243], v153 offset:10240
	s_waitcnt lgkmcnt(6)
	v_mfma_f32_32x32x16_bf16 v[64:79], v[224:227], v[96:99], v[64:79]
	v_add_f32_e32 v244, v145, v244
	v_permlane32_swap_b32_e32 v229, v231
	v_add_f32_e32 v187, v187, v244
	ds_read_b64_tr_b16 v[204:205], v153 offset:12288
	ds_read_b64_tr_b16 v[206:207], v153 offset:14336
	s_waitcnt lgkmcnt(6)
	v_mfma_f32_32x32x16_bf16 v[0:15], v[136:139], v[232:235], v[0:15]
	ds_read_b64_tr_b16 v[232:233], v153 offset:512
	ds_read_b64_tr_b16 v[234:235], v153 offset:2560
	v_fmamk_f32 v80, v80, 0x3e0293ee, v152
	v_fmamk_f32 v81, v81, 0x3e0293ee, v152
	v_fmamk_f32 v82, v82, 0x3e0293ee, v152
	v_fmamk_f32 v83, v83, 0x3e0293ee, v152
	s_waitcnt lgkmcnt(6)
	v_mfma_f32_32x32x16_bf16 v[0:15], v[140:143], v[236:239], v[0:15]
	ds_read_b64_tr_b16 v[236:237], v153 offset:4608
	ds_read_b64_tr_b16 v[238:239], v153 offset:6656
	v_fmamk_f32 v84, v84, 0x3e0293ee, v152
	v_fmamk_f32 v85, v85, 0x3e0293ee, v152
	v_fmamk_f32 v86, v86, 0x3e0293ee, v152
	v_fmamk_f32 v87, v87, 0x3e0293ee, v152
	s_waitcnt lgkmcnt(6)
	v_mfma_f32_32x32x16_bf16 v[0:15], v[208:211], v[240:243], v[0:15]
	ds_read_b64_tr_b16 v[240:241], v153 offset:8704
	ds_read_b64_tr_b16 v[242:243], v153 offset:10752
	v_fmamk_f32 v88, v88, 0x3e0293ee, v152
	v_fmamk_f32 v89, v89, 0x3e0293ee, v152
	v_fmamk_f32 v90, v90, 0x3e0293ee, v152
	v_fmamk_f32 v91, v91, 0x3e0293ee, v152
	s_waitcnt lgkmcnt(6)
	v_mfma_f32_32x32x16_bf16 v[0:15], v[228:231], v[204:207], v[0:15]
	ds_read_b64_tr_b16 v[204:205], v153 offset:12800
	ds_read_b64_tr_b16 v[206:207], v153 offset:14848
	v_fmamk_f32 v92, v92, 0x3e0293ee, v152
	v_fmamk_f32 v93, v93, 0x3e0293ee, v152
	v_fmamk_f32 v94, v94, 0x3e0293ee, v152
	v_fmamk_f32 v95, v95, 0x3e0293ee, v152
	s_waitcnt lgkmcnt(6)
	v_mfma_f32_32x32x16_bf16 v[16:31], v[136:139], v[232:235], v[16:31]
	ds_read_b64_tr_b16 v[232:233], v153 offset:1024
	ds_read_b64_tr_b16 v[234:235], v153 offset:3072
	v_exp_f32_e32 v199, v80
	v_fmamk_f32 v168, v64, 0x3e0293ee, v152
	v_exp_f32_e32 v201, v81
	v_fmamk_f32 v169, v65, 0x3e0293ee, v152
	s_waitcnt lgkmcnt(6)
; #define SBAR() __builtin_amdgcn_sched_barrier(0)
; #define SWRITE0(b) do { *(bf16x8*)((char*)V_lds + (b) * SHM_V + vst0) = s0_vs0; *(bf16x8*)((char*)V_lds + (b) * SHM_V + vst1) = s0_vs1; const int kc = sc * 2; \
;     *(bf16x8*)((char*)K_lds + (b) * SHM_K + KSWZ(sr, kc)) = s0_ks0; *(bf16x8*)((char*)K_lds + (b) * SHM_K + KSWZ(32 + sr, kc)) = s0_ks1; } while (0)
; #define SWAIT() asm volatile("s_waitcnt vmcnt(0)" ::: "memory")
; template <int D0> __device__ __forceinline__ void pv_one(f32x16& od, int vb, bf16x8 pa0, bf16x8 pa1, bf16x8 pa2, bf16x8 pa3) {
;   const s16x4 l0 = tr_read<v_rd_off(D0, 0, 0)>(vb), h0 = tr_read<v_rd_off(D0, 0, 1)>(vb), l1 = tr_read<v_rd_off(D0, 1, 0)>(vb), h1 = tr_read<v_rd_off(D0, 1, 1)>(vb);
;   const s16x4 l2 = tr_read<v_rd_off(D0, 2, 0)>(vb), h2 = tr_read<v_rd_off(D0, 2, 1)>(vb), l3 = tr_read<v_rd_off(D0, 3, 0)>(vb), h3 = tr_read<v_rd_off(D0, 3, 1)>(vb);
;   asm volatile("s_waitcnt lgkmcnt(0)" ::: "memory"); SBAR();
;     ...
;   od = __builtin_amdgcn_mfma_f32_32x32x16_bf16(pa0, PK(l0, h0), od, 0, 0, 0);
;   od = __builtin_amdgcn_mfma_f32_32x32x16_bf16(pa1, PK(l1, h1), od, 0, 0, 0);
;   od = __builtin_amdgcn_mfma_f32_32x32x16_bf16(pa2, PK(l2, h2), od, 0, 0, 0);
;   od = __builtin_amdgcn_mfma_f32_32x32x16_bf16(pa3, PK(l3, h3), od, 0, 0, 0);
;     ...
; }
; __device__ __forceinline__ void pv_d0(f32x16* o, int vb, bf16x8 pa0, bf16x8 pa1, bf16x8 pa2, bf16x8 pa3) {
;   pv_one<0>(o[0], vb, pa0, pa1, pa2, pa3); pv_one<1>(o[1], vb, pa0, pa1, pa2, pa3); pv_one<2>(o[2], vb, pa0, pa1, pa2, pa3); pv_one<3>(o[3], vb, pa0, pa1, pa2, pa3);
; }
; __device__ __forceinline__ void attn_dense_body(const bf16* __restrict__ Qb, const bf16* __restrict__ Kh, const bf16* __restrict__ Vh,
;                                                 bf16* __restrict__ Ob, int seq, char* lds, const int tid, const float mnC) {
;     ...
;     __syncthreads(); SWAIT(); SWRITE0(1);
;     SBAR(); __syncthreads();
;   }
;   SBAR(); qkt(pB0, pB1, (bf16*)((char*)K_lds + SHM_K), qr, r32, hi);
;   finishSM(pA0, pA1, l_reg, pa0, pa1, pa2, pa3); SBAR();
;   pv_d0(o, vb0, pa0, pa1, pa2, pa3); partialSM(pB0, pB1, mnC);
	v_mfma_f32_32x32x16_bf16 v[16:31], v[140:143], v[236:239], v[16:31]
	ds_read_b64_tr_b16 v[236:237], v153 offset:5120
	ds_read_b64_tr_b16 v[238:239], v153 offset:7168
	v_exp_f32_e32 v198, v82
	v_fmamk_f32 v166, v66, 0x3e0293ee, v152
	v_exp_f32_e32 v203, v83
	v_fmamk_f32 v167, v67, 0x3e0293ee, v152
	s_waitcnt lgkmcnt(6)
	v_mfma_f32_32x32x16_bf16 v[16:31], v[208:211], v[240:243], v[16:31]
	ds_read_b64_tr_b16 v[240:241], v153 offset:9216
	ds_read_b64_tr_b16 v[242:243], v153 offset:11264
	v_exp_f32_e32 v200, v84
	v_fmamk_f32 v164, v68, 0x3e0293ee, v152
	v_exp_f32_e32 v202, v85
	v_fmamk_f32 v165, v69, 0x3e0293ee, v152
	s_waitcnt lgkmcnt(6)
	v_mfma_f32_32x32x16_bf16 v[16:31], v[228:231], v[204:207], v[16:31]
	ds_read_b64_tr_b16 v[204:205], v153 offset:13312
	ds_read_b64_tr_b16 v[206:207], v153 offset:15360
	v_exp_f32_e32 v196, v86
	v_fmamk_f32 v150, v70, 0x3e0293ee, v152
	v_exp_f32_e32 v197, v87
	v_fmamk_f32 v151, v71, 0x3e0293ee, v152
	s_waitcnt lgkmcnt(6)
	v_mfma_f32_32x32x16_bf16 v[32:47], v[136:139], v[232:235], v[32:47]
	ds_read_b64_tr_b16 v[232:233], v153 offset:1536
	ds_read_b64_tr_b16 v[234:235], v153 offset:3584
	v_exp_f32_e32 v193, v88
	v_fmamk_f32 v162, v72, 0x3e0293ee, v152
	v_exp_f32_e32 v195, v89
	v_fmamk_f32 v163, v73, 0x3e0293ee, v152
	s_waitcnt lgkmcnt(6)
	v_mfma_f32_32x32x16_bf16 v[32:47], v[140:143], v[236:239], v[32:47]
	ds_read_b64_tr_b16 v[236:237], v153 offset:5632
	ds_read_b64_tr_b16 v[238:239], v153 offset:7680
	v_exp_f32_e32 v192, v90
	v_fmamk_f32 v148, v74, 0x3e0293ee, v152
	v_exp_f32_e32 v194, v91
	v_fmamk_f32 v149, v75, 0x3e0293ee, v152
	s_waitcnt lgkmcnt(6)
	v_mfma_f32_32x32x16_bf16 v[32:47], v[208:211], v[240:243], v[32:47]
	ds_read_b64_tr_b16 v[240:241], v153 offset:9728
	ds_read_b64_tr_b16 v[242:243], v153 offset:11776
	v_exp_f32_e32 v189, v92
	v_fmamk_f32 v146, v76, 0x3e0293ee, v152
	v_exp_f32_e32 v191, v93
	v_fmamk_f32 v147, v77, 0x3e0293ee, v152
	s_waitcnt lgkmcnt(6)
	v_mfma_f32_32x32x16_bf16 v[32:47], v[228:231], v[204:207], v[32:47]
	ds_read_b64_tr_b16 v[204:205], v153 offset:13824
	ds_read_b64_tr_b16 v[206:207], v153 offset:15872
	v_exp_f32_e32 v188, v94
	v_fmamk_f32 v144, v78, 0x3e0293ee, v152
	v_exp_f32_e32 v190, v95
	v_fmamk_f32 v145, v79, 0x3e0293ee, v152
	s_add_i32 s12, s12, 2
	s_cmpk_gt_u32 s12, 0x80
	s_waitcnt vmcnt(0) lgkmcnt(0)
	s_barrier
	s_cbranch_scc0 .LBB0_1040
	v_mfma_f32_32x32x16_bf16 v[48:63], v[136:139], v[232:235], v[48:63]
	v_mfma_f32_32x32x16_bf16 v[48:63], v[140:143], v[236:239], v[48:63]
	v_mfma_f32_32x32x16_bf16 v[48:63], v[208:211], v[240:243], v[48:63]
	v_mfma_f32_32x32x16_bf16 v[48:63], v[228:231], v[204:207], v[48:63]
	s_add_i32 m0, s98, 0x4000
	s_nop 0
	global_load_lds_dwordx4 v218, s[16:17]
	s_add_i32 m0, s98, 0x4400
	s_nop 0
	global_load_lds_dwordx4 v219, s[16:17]
	s_waitcnt vmcnt(0)
	s_barrier
	v_and_b32_e32 v64, 0x3fffffc0, v174
	s_add_i32 s12, 0, 0x10000
	v_lshl_add_u32 v128, v64, 2, s12
	ds_read_b128 v[64:67], v179 offset:49152
	ds_read_b128 v[68:71], v179 offset:57344
	s_waitcnt lgkmcnt(1)
	v_mfma_f32_32x32x16_bf16 v[80:95], v[64:67], v[124:127], 0
	s_waitcnt lgkmcnt(0)
	v_mfma_f32_32x32x16_bf16 v[64:79], v[68:71], v[124:127], 0
	ds_read_b128 v[124:127], v182 offset:49152
	ds_read_b128 v[130:133], v182 offset:57344
	s_waitcnt lgkmcnt(1)
	v_mfma_f32_32x32x16_bf16 v[80:95], v[124:127], v[120:123], v[80:95]
	s_waitcnt lgkmcnt(0)
	v_mfma_f32_32x32x16_bf16 v[64:79], v[130:133], v[120:123], v[64:79]
	ds_read_b128 v[120:123], v183 offset:49152
	ds_read_b128 v[124:127], v183 offset:57344
	s_waitcnt lgkmcnt(1)
	v_mfma_f32_32x32x16_bf16 v[80:95], v[120:123], v[116:119], v[80:95]
	s_waitcnt lgkmcnt(0)
	v_mfma_f32_32x32x16_bf16 v[64:79], v[124:127], v[116:119], v[64:79]
	ds_read_b128 v[116:119], v184 offset:49152
	ds_read_b128 v[120:123], v184 offset:57344
	s_waitcnt lgkmcnt(1)
	v_mfma_f32_32x32x16_bf16 v[80:95], v[116:119], v[112:115], v[80:95]
	s_waitcnt lgkmcnt(0)
	v_mfma_f32_32x32x16_bf16 v[64:79], v[120:123], v[112:115], v[64:79]
	ds_read_b128 v[112:115], v185 offset:49152
	ds_read_b128 v[116:119], v185 offset:57344
	s_waitcnt lgkmcnt(1)
	v_mfma_f32_32x32x16_bf16 v[80:95], v[112:115], v[108:111], v[80:95]
	s_waitcnt lgkmcnt(0)
	v_mfma_f32_32x32x16_bf16 v[64:79], v[116:119], v[108:111], v[64:79]
	ds_read_b128 v[108:111], v186 offset:49152
	ds_read_b128 v[112:115], v186 offset:57344
	v_exp_f32_e32 v116, v146
	v_exp_f32_e32 v117, v147
	v_exp_f32_e32 v118, v144
	v_exp_f32_e32 v119, v145
	s_waitcnt lgkmcnt(1)
	v_mfma_f32_32x32x16_bf16 v[80:95], v[108:111], v[104:107], v[80:95]
	s_waitcnt lgkmcnt(0)
	v_mfma_f32_32x32x16_bf16 v[64:79], v[112:115], v[104:107], v[64:79]
	ds_read_b128 v[104:107], v180 offset:49152
	ds_read_b128 v[108:111], v180 offset:57344
	v_exp_f32_e32 v112, v162
	v_exp_f32_e32 v113, v163
	v_exp_f32_e32 v114, v148
	v_exp_f32_e32 v115, v149
	s_waitcnt lgkmcnt(1)
	v_mfma_f32_32x32x16_bf16 v[80:95], v[104:107], v[100:103], v[80:95]
	s_waitcnt lgkmcnt(0)
	v_mfma_f32_32x32x16_bf16 v[64:79], v[108:111], v[100:103], v[64:79]
	ds_read_b128 v[100:103], v181 offset:49152
	ds_read_b128 v[104:107], v181 offset:57344
	v_exp_f32_e32 v108, v164
	v_exp_f32_e32 v109, v165
	v_exp_f32_e32 v110, v150
	v_exp_f32_e32 v111, v151
	s_waitcnt lgkmcnt(1)
	v_mfma_f32_32x32x16_bf16 v[80:95], v[100:103], v[96:99], v[80:95]
	s_waitcnt lgkmcnt(0)
; #define SBAR() __builtin_amdgcn_sched_barrier(0)
; __device__ __forceinline__ void finishSM(f32x16& p0, f32x16& p1, float& l_reg, bf16x8& pa0, bf16x8& pa1, bf16x8& pa2, bf16x8& pa3) {
; #pragma unroll
;   for (int r = 0; r < 16; ++r) p1[r] = __builtin_amdgcn_exp2f(p1[r]);
;   float ps = 0;
; #pragma unroll
;   for (int r = 0; r < 16; ++r) ps += p0[r];
; #pragma unroll
;   for (int r = 0; r < 16; ++r) ps += p1[r];
;   l_reg += ps;
;     ...
;   PK4(p0, 0, pa0); PK4(p0, 8, pa1); PK4(p1, 0, pa2); PK4(p1, 8, pa3);
;     ...
; }
; __device__ __forceinline__ void qkt(f32x16& p0, f32x16& p1, const bf16* Ks, const bf16x8* qr, int r32, int hi) {
;   p0 = f32x16{}; p1 = f32x16{};
; #pragma unroll
;   for (int d0 = 0; d0 < 8; ++d0) { int cb = (d0 * 16 + hi * 8) * 2;
;     bf16x8 b0 = *reinterpret_cast<const bf16x8*>((const char*)Ks + KSWZ(r32, cb));
;     bf16x8 b1 = *reinterpret_cast<const bf16x8*>((const char*)Ks + KSWZ(32 + r32, cb));
;     p0 = __builtin_amdgcn_mfma_f32_32x32x16_bf16(b0, qr[d0], p0, 0, 0, 0);
;     p1 = __builtin_amdgcn_mfma_f32_32x32x16_bf16(b1, qr[d0], p1, 0, 0, 0); }
; }
; __device__ __forceinline__ int v_st(int k, int c) { const int kk = (k & ~0xC) | ((k & 4) << 1) | ((k & 8) >> 1); return ((kk >> 3) * 4 + (c >> 5)) * 512 + ((kk & 7) * 32 + (c & 31)) * 2; }
; __device__ __forceinline__ int v_rd_base(int lane) { return ((lane & 3) << 3) | (((lane >> 2) & 3) << 6) | (((lane >> 4) & 1) << 5) | (((lane >> 5) & 1) << 8); }
; template <int OFF> __device__ __forceinline__ s16x4 tr_read(int vb) {
;   s16x4 r; asm volatile("ds_read_b64_tr_b16 %0, %1 offset:%2" : "=&v"(r) : "v"(vb), "i"(OFF) : "memory"); return r;
; }
; template <int D0> __device__ __forceinline__ void pv_one(f32x16& od, int vb, bf16x8 pa0, bf16x8 pa1, bf16x8 pa2, bf16x8 pa3) {
;   const s16x4 l0 = tr_read<v_rd_off(D0, 0, 0)>(vb), h0 = tr_read<v_rd_off(D0, 0, 1)>(vb), l1 = tr_read<v_rd_off(D0, 1, 0)>(vb), h1 = tr_read<v_rd_off(D0, 1, 1)>(vb);
;   const s16x4 l2 = tr_read<v_rd_off(D0, 2, 0)>(vb), h2 = tr_read<v_rd_off(D0, 2, 1)>(vb), l3 = tr_read<v_rd_off(D0, 3, 0)>(vb), h3 = tr_read<v_rd_off(D0, 3, 1)>(vb);
;   asm volatile("s_waitcnt lgkmcnt(0)" ::: "memory"); SBAR();
;     ...
;   od = __builtin_amdgcn_mfma_f32_32x32x16_bf16(pa0, PK(l0, h0), od, 0, 0, 0);
;   od = __builtin_amdgcn_mfma_f32_32x32x16_bf16(pa1, PK(l1, h1), od, 0, 0, 0);
;   od = __builtin_amdgcn_mfma_f32_32x32x16_bf16(pa2, PK(l2, h2), od, 0, 0, 0);
	v_mfma_f32_32x32x16_bf16 v[64:79], v[104:107], v[96:99], v[64:79]
	v_add_f32_e32 v96, 0, v199
	v_add_f32_e32 v96, v201, v96
	v_add_f32_e32 v96, v198, v96
	v_add_f32_e32 v96, v203, v96
	v_add_f32_e32 v96, v200, v96
	v_add_f32_e32 v96, v202, v96
	v_add_f32_e32 v96, v196, v96
	v_add_f32_e32 v96, v197, v96
	v_add_f32_e32 v96, v193, v96
	v_add_f32_e32 v96, v195, v96
	v_add_f32_e32 v96, v192, v96
	v_add_f32_e32 v96, v194, v96
	v_exp_f32_e32 v104, v168
	v_add_f32_e32 v96, v189, v96
	v_exp_f32_e32 v105, v169
	v_add_f32_e32 v96, v191, v96
	v_exp_f32_e32 v106, v166
	v_add_f32_e32 v96, v188, v96
	v_exp_f32_e32 v107, v167
	v_add_f32_e32 v96, v190, v96
	v_add_f32_e32 v96, v104, v96
	v_add_f32_e32 v96, v105, v96
	v_add_f32_e32 v96, v106, v96
	v_add_f32_e32 v96, v107, v96
	v_add_f32_e32 v96, v108, v96
	v_add_f32_e32 v96, v109, v96
	v_add_f32_e32 v96, v110, v96
	v_add_f32_e32 v96, v111, v96
	v_add_f32_e32 v96, v112, v96
	v_add_f32_e32 v96, v113, v96
	v_add_f32_e32 v96, v114, v96
	v_add_f32_e32 v96, v115, v96
	v_add_f32_e32 v96, v116, v96
	v_add_f32_e32 v96, v117, v96
	v_add_f32_e32 v96, v118, v96
	v_add_f32_e32 v96, v119, v96
	v_add_f32_e32 v129, v187, v96
	v_cvt_pk_bf16_f32 v96, v199, v201
	v_cvt_pk_bf16_f32 v97, v198, v203
	v_cvt_pk_bf16_f32 v98, v200, v202
	v_cvt_pk_bf16_f32 v99, v196, v197
	v_cvt_pk_bf16_f32 v100, v193, v195
	v_cvt_pk_bf16_f32 v101, v192, v194
	v_cvt_pk_bf16_f32 v102, v189, v191
	v_cvt_pk_bf16_f32 v103, v188, v190
	v_cvt_pk_bf16_f32 v104, v104, v105
	v_cvt_pk_bf16_f32 v105, v106, v107
	v_cvt_pk_bf16_f32 v106, v108, v109
	v_cvt_pk_bf16_f32 v107, v110, v111
	v_cvt_pk_bf16_f32 v108, v112, v113
	v_cvt_pk_bf16_f32 v109, v114, v115
	v_cvt_pk_bf16_f32 v110, v116, v117
	v_cvt_pk_bf16_f32 v111, v118, v119
	s_nop 0
	v_permlane32_swap_b32_e32 v96, v98
	v_permlane32_swap_b32_e32 v97, v99
	v_permlane32_swap_b32_e32 v100, v102
	v_permlane32_swap_b32_e32 v101, v103
	v_permlane32_swap_b32_e32 v104, v106
	v_permlane32_swap_b32_e32 v105, v107
	v_permlane32_swap_b32_e32 v108, v110
	v_permlane32_swap_b32_e32 v109, v111
	ds_read_b64_tr_b16 v[112:113], v173 offset:0
	ds_read_b64_tr_b16 v[114:115], v173 offset:0x800
	ds_read_b64_tr_b16 v[116:117], v173 offset:0x1000
	ds_read_b64_tr_b16 v[118:119], v173 offset:0x1800
	ds_read_b64_tr_b16 v[120:121], v173 offset:0x2000
	ds_read_b64_tr_b16 v[122:123], v173 offset:0x2800
	ds_read_b64_tr_b16 v[124:125], v173 offset:0x3000
	ds_read_b64_tr_b16 v[126:127], v173 offset:0x3800
	s_waitcnt lgkmcnt(0)
	s_nop 0
	v_mfma_f32_32x32x16_bf16 v[0:15], v[96:99], v[112:115], v[0:15]
	ds_read_b64_tr_b16 v[112:113], v173 offset:0x200
	ds_read_b64_tr_b16 v[114:115], v173 offset:0xa00
	v_mfma_f32_32x32x16_bf16 v[0:15], v[100:103], v[116:119], v[0:15]
	ds_read_b64_tr_b16 v[116:117], v173 offset:0x1200
	ds_read_b64_tr_b16 v[118:119], v173 offset:0x1a00
	v_mfma_f32_32x32x16_bf16 v[0:15], v[104:107], v[120:123], v[0:15]
	ds_read_b64_tr_b16 v[120:121], v173 offset:0x2200
	ds_read_b64_tr_b16 v[122:123], v173 offset:0x2a00
	v_mfma_f32_32x32x16_bf16 v[0:15], v[108:111], v[124:127], v[0:15]
	ds_read_b64_tr_b16 v[124:125], v173 offset:0x3200
	ds_read_b64_tr_b16 v[126:127], v173 offset:0x3a00
	s_waitcnt lgkmcnt(0)
	v_mfma_f32_32x32x16_bf16 v[16:31], v[96:99], v[112:115], v[16:31]
	ds_read_b64_tr_b16 v[112:113], v173 offset:0x400
	ds_read_b64_tr_b16 v[114:115], v173 offset:0xc00
	v_mfma_f32_32x32x16_bf16 v[16:31], v[100:103], v[116:119], v[16:31]
	ds_read_b64_tr_b16 v[116:117], v173 offset:0x1400
	ds_read_b64_tr_b16 v[118:119], v173 offset:0x1c00
	v_mfma_f32_32x32x16_bf16 v[16:31], v[104:107], v[120:123], v[16:31]
	ds_read_b64_tr_b16 v[120:121], v173 offset:0x2400
	ds_read_b64_tr_b16 v[122:123], v173 offset:0x2c00
	v_mfma_f32_32x32x16_bf16 v[16:31], v[108:111], v[124:127], v[16:31]
	ds_read_b64_tr_b16 v[124:125], v173 offset:0x3400
	ds_read_b64_tr_b16 v[126:127], v173 offset:0x3c00
	s_waitcnt lgkmcnt(0)
	v_mfma_f32_32x32x16_bf16 v[32:47], v[96:99], v[112:115], v[32:47]
	ds_read_b64_tr_b16 v[112:113], v173 offset:0x600
	ds_read_b64_tr_b16 v[114:115], v173 offset:0xe00
	v_mfma_f32_32x32x16_bf16 v[32:47], v[100:103], v[116:119], v[32:47]
	ds_read_b64_tr_b16 v[116:117], v173 offset:0x1600
	ds_read_b64_tr_b16 v[118:119], v173 offset:0x1e00
	v_mfma_f32_32x32x16_bf16 v[32:47], v[104:107], v[120:123], v[32:47]
	ds_read_b64_tr_b16 v[120:121], v173 offset:0x2600
	ds_read_b64_tr_b16 v[122:123], v173 offset:0x2e00
	v_mfma_f32_32x32x16_bf16 v[32:47], v[108:111], v[124:127], v[32:47]
	ds_read_b64_tr_b16 v[124:125], v173 offset:0x3600
	ds_read_b64_tr_b16 v[126:127], v173 offset:0x3e00
	s_waitcnt lgkmcnt(0)
; __device__ __forceinline__ void partialSM(f32x16& p0, f32x16& p1, float mnC) {
;   constexpr float C = SCALE * 1.4426950408889634f;
; #pragma unroll
;   for (int r = 0; r < 16; ++r) p0[r] = fmaf(p0[r], C, mnC);
; #pragma unroll
;   for (int r = 0; r < 16; ++r) p1[r] = fmaf(p1[r], C, mnC);
; #pragma unroll
;   for (int r = 0; r < 16; ++r) p0[r] = __builtin_amdgcn_exp2f(p0[r]);
; }
; __device__ __forceinline__ void finishSM(f32x16& p0, f32x16& p1, float& l_reg, bf16x8& pa0, bf16x8& pa1, bf16x8& pa2, bf16x8& pa3) {
; #pragma unroll
;   for (int r = 0; r < 16; ++r) p1[r] = __builtin_amdgcn_exp2f(p1[r]);
;   float ps = 0;
; #pragma unroll
;   for (int r = 0; r < 16; ++r) ps += p0[r];
; #pragma unroll
;   for (int r = 0; r < 16; ++r) ps += p1[r];
;   l_reg += ps;
	v_fmamk_f32 v80, v80, 0x3e0293ee, v152
	v_fmamk_f32 v81, v81, 0x3e0293ee, v152
	v_exp_f32_e32 v80, v80
	v_fmamk_f32 v82, v82, 0x3e0293ee, v152
	v_exp_f32_e32 v81, v81
	v_fmamk_f32 v83, v83, 0x3e0293ee, v152
	v_exp_f32_e32 v82, v82
	v_fmamk_f32 v84, v84, 0x3e0293ee, v152
	v_fmamk_f32 v64, v64, 0x3e0293ee, v152
	v_exp_f32_e32 v83, v83
	v_mfma_f32_32x32x16_bf16 v[48:63], v[96:99], v[112:115], v[48:63]
	v_fmamk_f32 v85, v85, 0x3e0293ee, v152
	v_exp_f32_e32 v84, v84
	v_exp_f32_e32 v96, v64
	v_add_f32_e32 v64, 0, v80
	v_fmamk_f32 v86, v86, 0x3e0293ee, v152
	v_exp_f32_e32 v85, v85
	v_add_f32_e32 v64, v81, v64
	v_fmamk_f32 v87, v87, 0x3e0293ee, v152
	v_exp_f32_e32 v86, v86
	v_add_f32_e32 v64, v82, v64
	v_fmamk_f32 v88, v88, 0x3e0293ee, v152
	v_exp_f32_e32 v87, v87
	v_add_f32_e32 v64, v83, v64
	v_fmamk_f32 v89, v89, 0x3e0293ee, v152
	v_exp_f32_e32 v88, v88
	v_add_f32_e32 v64, v84, v64
	v_fmamk_f32 v90, v90, 0x3e0293ee, v152
	v_exp_f32_e32 v89, v89
	v_add_f32_e32 v64, v85, v64
	v_fmamk_f32 v91, v91, 0x3e0293ee, v152
	v_exp_f32_e32 v90, v90
	v_add_f32_e32 v64, v86, v64
	v_fmamk_f32 v92, v92, 0x3e0293ee, v152
	v_exp_f32_e32 v91, v91
	v_add_f32_e32 v64, v87, v64
	v_fmamk_f32 v93, v93, 0x3e0293ee, v152
	v_exp_f32_e32 v92, v92
	v_add_f32_e32 v64, v88, v64
	v_mfma_f32_32x32x16_bf16 v[48:63], v[100:103], v[116:119], v[48:63]
	v_fmamk_f32 v94, v94, 0x3e0293ee, v152
	v_exp_f32_e32 v93, v93
	v_add_f32_e32 v64, v89, v64
	v_fmamk_f32 v95, v95, 0x3e0293ee, v152
	v_exp_f32_e32 v94, v94
	v_add_f32_e32 v64, v90, v64
	v_exp_f32_e32 v95, v95
	v_add_f32_e32 v64, v91, v64
	v_fmamk_f32 v65, v65, 0x3e0293ee, v152
	v_add_f32_e32 v64, v92, v64
	v_fmamk_f32 v66, v66, 0x3e0293ee, v152
	v_exp_f32_e32 v65, v65
	v_add_f32_e32 v64, v93, v64
	v_fmamk_f32 v67, v67, 0x3e0293ee, v152
	v_exp_f32_e32 v97, v66
	v_add_f32_e32 v64, v94, v64
	v_fmamk_f32 v68, v68, 0x3e0293ee, v152
	v_exp_f32_e32 v98, v67
	v_add_f32_e32 v64, v95, v64
	v_fmamk_f32 v69, v69, 0x3e0293ee, v152
	v_exp_f32_e32 v99, v68
	v_add_f32_e32 v64, v96, v64
	v_mfma_f32_32x32x16_bf16 v[48:63], v[104:107], v[120:123], v[48:63]
	v_fmamk_f32 v70, v70, 0x3e0293ee, v152
	v_exp_f32_e32 v100, v69
	v_add_f32_e32 v64, v65, v64
	v_fmamk_f32 v71, v71, 0x3e0293ee, v152
	v_exp_f32_e32 v101, v70
	v_add_f32_e32 v64, v97, v64
	v_fmamk_f32 v72, v72, 0x3e0293ee, v152
	v_exp_f32_e32 v102, v71
	v_add_f32_e32 v64, v98, v64
	v_fmamk_f32 v73, v73, 0x3e0293ee, v152
	v_exp_f32_e32 v103, v72
	v_add_f32_e32 v64, v99, v64
	v_fmamk_f32 v74, v74, 0x3e0293ee, v152
	v_exp_f32_e32 v104, v73
	v_add_f32_e32 v64, v100, v64
	v_fmamk_f32 v75, v75, 0x3e0293ee, v152
	v_exp_f32_e32 v105, v74
	v_add_f32_e32 v64, v101, v64
	v_fmamk_f32 v76, v76, 0x3e0293ee, v152
	v_exp_f32_e32 v106, v75
	v_add_f32_e32 v64, v102, v64
	v_fmamk_f32 v77, v77, 0x3e0293ee, v152
	v_exp_f32_e32 v107, v76
	v_add_f32_e32 v64, v103, v64
	v_mfma_f32_32x32x16_bf16 v[48:63], v[108:111], v[124:127], v[48:63]
	v_fmamk_f32 v78, v78, 0x3e0293ee, v152
	v_exp_f32_e32 v108, v77
	v_add_f32_e32 v64, v104, v64
	v_fmamk_f32 v79, v79, 0x3e0293ee, v152
	v_exp_f32_e32 v109, v78
	v_add_f32_e32 v64, v105, v64
	v_exp_f32_e32 v110, v79
	v_add_f32_e32 v64, v106, v64
	v_add_f32_e32 v64, v107, v64
	v_add_f32_e32 v64, v108, v64
	v_add_f32_e32 v64, v109, v64
	v_add_f32_e32 v64, v110, v64
	s_barrier
; #define SBAR() __builtin_amdgcn_sched_barrier(0)
; __device__ __forceinline__ void finishSM(f32x16& p0, f32x16& p1, float& l_reg, bf16x8& pa0, bf16x8& pa1, bf16x8& pa2, bf16x8& pa3) {
;     ...
;   PK4(p0, 0, pa0); PK4(p0, 8, pa1); PK4(p1, 0, pa2); PK4(p1, 8, pa3);
;     ...
; }
; __device__ __forceinline__ void attn_dense_body(const bf16* __restrict__ Qb, const bf16* __restrict__ Kh, const bf16* __restrict__ Vh,
;                                                 bf16* __restrict__ Ob, int seq, char* lds, const int tid, const float mnC) {
;     ...
;   finishSM(pB0, pB1, l_reg, pa0, pa1, pa2, pa3); SBAR();
;   pv_d0(o, vb0 + (int)SHM_V, pa0, pa1, pa2, pa3);
;   { auto rr = __builtin_amdgcn_permlane32_swap(__float_as_uint(l_reg), __float_as_uint(l_reg), false, false);
;     l_reg = __uint_as_float(rr[0]) + __uint_as_float(rr[1]); }
;   __builtin_amdgcn_s_setprio(0);
;   if (hi == 0) li_l[r32] = l_reg; asm volatile("s_waitcnt lgkmcnt(0)" ::: "memory");
	v_add_f32_e32 v64, v129, v64
	v_cvt_pk_bf16_f32 v66, v80, v81
	v_cvt_pk_bf16_f32 v67, v82, v83
	v_cvt_pk_bf16_f32 v68, v84, v85
	v_cvt_pk_bf16_f32 v69, v86, v87
	v_cvt_pk_bf16_f32 v70, v88, v89
	v_cvt_pk_bf16_f32 v71, v90, v91
	v_cvt_pk_bf16_f32 v72, v92, v93
	v_cvt_pk_bf16_f32 v73, v94, v95
	v_cvt_pk_bf16_f32 v74, v96, v65
	v_cvt_pk_bf16_f32 v75, v97, v98
	v_cvt_pk_bf16_f32 v76, v99, v100
	v_cvt_pk_bf16_f32 v77, v101, v102
	v_cvt_pk_bf16_f32 v78, v103, v104
	v_cvt_pk_bf16_f32 v79, v105, v106
	v_cvt_pk_bf16_f32 v80, v107, v108
	v_cvt_pk_bf16_f32 v81, v109, v110
	s_nop 0
	v_permlane32_swap_b32_e32 v66, v68
	v_permlane32_swap_b32_e32 v67, v69
	v_permlane32_swap_b32_e32 v70, v72
	v_permlane32_swap_b32_e32 v71, v73
	v_permlane32_swap_b32_e32 v74, v76
	v_permlane32_swap_b32_e32 v75, v77
	v_permlane32_swap_b32_e32 v78, v80
	v_permlane32_swap_b32_e32 v79, v81
	ds_read_b64_tr_b16 v[82:83], v153 offset:0
	ds_read_b64_tr_b16 v[84:85], v153 offset:0x800
	ds_read_b64_tr_b16 v[86:87], v153 offset:0x1000
	ds_read_b64_tr_b16 v[88:89], v153 offset:0x1800
	ds_read_b64_tr_b16 v[90:91], v153 offset:0x2000
	ds_read_b64_tr_b16 v[92:93], v153 offset:0x2800
	ds_read_b64_tr_b16 v[94:95], v153 offset:0x3000
	ds_read_b64_tr_b16 v[96:97], v153 offset:0x3800
	s_waitcnt lgkmcnt(0)
	s_nop 0
	v_mfma_f32_32x32x16_bf16 v[0:15], v[66:69], v[82:85], v[0:15]
	ds_read_b64_tr_b16 v[82:83], v153 offset:0x200
	ds_read_b64_tr_b16 v[84:85], v153 offset:0xa00
	v_mfma_f32_32x32x16_bf16 v[0:15], v[70:73], v[86:89], v[0:15]
	ds_read_b64_tr_b16 v[86:87], v153 offset:0x1200
	ds_read_b64_tr_b16 v[88:89], v153 offset:0x1a00
	v_mfma_f32_32x32x16_bf16 v[0:15], v[74:77], v[90:93], v[0:15]
	ds_read_b64_tr_b16 v[90:91], v153 offset:0x2200
	ds_read_b64_tr_b16 v[92:93], v153 offset:0x2a00
	v_mfma_f32_32x32x16_bf16 v[0:15], v[78:81], v[94:97], v[0:15]
	ds_read_b64_tr_b16 v[94:95], v153 offset:0x3200
	ds_read_b64_tr_b16 v[96:97], v153 offset:0x3a00
	s_waitcnt lgkmcnt(0)
	v_mfma_f32_32x32x16_bf16 v[16:31], v[66:69], v[82:85], v[16:31]
	ds_read_b64_tr_b16 v[82:83], v153 offset:0x400
	ds_read_b64_tr_b16 v[84:85], v153 offset:0xc00
	v_mfma_f32_32x32x16_bf16 v[16:31], v[70:73], v[86:89], v[16:31]
	ds_read_b64_tr_b16 v[86:87], v153 offset:0x1400
	ds_read_b64_tr_b16 v[88:89], v153 offset:0x1c00
	v_mfma_f32_32x32x16_bf16 v[16:31], v[74:77], v[90:93], v[16:31]
	ds_read_b64_tr_b16 v[90:91], v153 offset:0x2400
	ds_read_b64_tr_b16 v[92:93], v153 offset:0x2c00
	v_mfma_f32_32x32x16_bf16 v[16:31], v[78:81], v[94:97], v[16:31]
	ds_read_b64_tr_b16 v[94:95], v153 offset:0x3400
	ds_read_b64_tr_b16 v[96:97], v153 offset:0x3c00
	s_waitcnt lgkmcnt(0)
	v_mfma_f32_32x32x16_bf16 v[32:47], v[66:69], v[82:85], v[32:47]
	ds_read_b64_tr_b16 v[82:83], v153 offset:0x600
	ds_read_b64_tr_b16 v[84:85], v153 offset:0xe00
	v_mfma_f32_32x32x16_bf16 v[32:47], v[70:73], v[86:89], v[32:47]
	ds_read_b64_tr_b16 v[86:87], v153 offset:0x1600
	ds_read_b64_tr_b16 v[88:89], v153 offset:0x1e00
	v_mfma_f32_32x32x16_bf16 v[32:47], v[74:77], v[90:93], v[32:47]
	ds_read_b64_tr_b16 v[90:91], v153 offset:0x2600
	ds_read_b64_tr_b16 v[92:93], v153 offset:0x2e00
	v_mfma_f32_32x32x16_bf16 v[32:47], v[78:81], v[94:97], v[32:47]
	ds_read_b64_tr_b16 v[94:95], v153 offset:0x3600
	ds_read_b64_tr_b16 v[96:97], v153 offset:0x3e00
	s_waitcnt lgkmcnt(0)
	v_mfma_f32_32x32x16_bf16 v[48:63], v[66:69], v[82:85], v[48:63]
	v_mov_b32_e32 v65, v64
	s_nop 1
	v_permlane32_swap_b32_e32 v64, v65
	v_mfma_f32_32x32x16_bf16 v[48:63], v[70:73], v[86:89], v[48:63]
	v_mfma_f32_32x32x16_bf16 v[48:63], v[74:77], v[90:93], v[48:63]
	v_mfma_f32_32x32x16_bf16 v[48:63], v[78:81], v[94:97], v[48:63]
	s_setprio 0
	v_cmp_gt_u32_e32 vcc, 32, v159
	s_and_saveexec_b64 s[12:13], vcc
	s_cbranch_execz .LBB0_1036
	v_add_f32_e32 v64, v64, v65
	v_lshl_add_u32 v65, v171, 2, v128
	ds_write_b32 v65, v64
	s_branch .LBB0_1036
